# plus: a quarter of each workgroup's bf16 residual tile kept in spare LDS (static +32752 B) across the residual-GEMM epilogues instead of global memory
# speedup vs baseline: 1.0046x; 1.0046x over previous
.LBB0_890:
	v_readlane_b32 s98, v254, 41
	v_readlane_b32 s99, v254, 51
	v_readlane_b32 s100, v254, 11
	s_or_b32 s98, s98, s99
	v_readlane_b32 s99, v254, 5
	s_cmp_lg_u32 s100, 0
	s_cselect_b32 s100, 0x4000, 0
	s_lshl_b32 s99, s99, 7
	s_add_u32 s99, s99, s100
	s_add_u32 s99, s99, 131088
	s_waitcnt vmcnt(0)
	s_cmpk_gt_u32 s31, 0xff
	s_cbranch_scc1 .LBB0_892
	s_barrier

.LBB0_894:
	s_add_u32 s10, s80, 0x5684100
	s_addc_u32 s11, s81, 0
	s_lshl_b32 s0, s2, 8
	v_readlane_b32 s1, v254, 5
	v_mbcnt_lo_u32_b32 v252, -1, 0
	v_mbcnt_hi_u32_b32 v252, -1, v252
	s_or_b32 s0, s0, s1
	v_lshrrev_b32_e32 v0, 1, v252
	v_and_or_b32 v242, v0, 24, s0
	s_mul_i32 s3, s16, 0xc0
	v_readlane_b32 s0, v254, 11
	s_add_i32 s14, s3, s0
	s_add_i32 s0, s3, 0xffffe000
	s_lshr_b32 s0, s0, 10
	s_add_i32 s12, s0, 1
	s_cmp_lt_i32 s16, 43
	s_cselect_b64 s[0:1], -1, 0
	s_and_b64 s[4:5], s[0:1], exec
	s_cselect_b32 s12, 0, s12
	s_add_i32 s4, s3, 0xffffe0bf
	s_lshr_b32 s4, s4, 10
	s_add_i32 s4, s4, 1
	v_and_b32_e32 v253, 15, v252
	s_cmp_eq_u32 s4, s12
	v_or_b32_e32 v249, s14, v253
	s_cselect_b64 s[4:5], -1, 0
	v_cndmask_b32_e64 v0, 0, 1, s[4:5]
	v_lshlrev_b32_e32 v118, 10, v249
	v_cndmask_b32_e64 v98, 0, 1, s[0:1]
	v_readfirstlane_b32 s1, v0
	v_add_u32_e32 v0, v118, v242
	v_readfirstlane_b32 s0, v98
	v_lshl_add_u64 v[98:99], v[0:1], 1, s[10:11]
	s_cmp_eq_u32 s98, 0
	s_cbranch_scc1 .Lxl_g_0
	v_mbcnt_lo_u32_b32 v98, -1, 0
	v_mbcnt_hi_u32_b32 v98, -1, v98
	v_lshl_add_u32 v98, v98, 4, s99
	ds_read_b128 v[190:193], v98
	s_branch .Lxl_d_0
.Lxl_g_0:
	global_load_dwordx4 v[190:193], v[98:99], off
.Lxl_d_0:
	v_add_u32_e32 v98, 0x4000, v0
	v_mov_b32_e32 v99, v1
	v_lshl_add_u64 v[98:99], v[98:99], 1, s[10:11]
	v_add_u32_e32 v0, 0x8000, v0
	v_add_u32_e32 v119, 0x18000, v118
	s_cmp_eq_u32 s98, 0
	s_cbranch_scc1 .Lxl_g_1
	v_mbcnt_lo_u32_b32 v98, -1, 0
	v_mbcnt_hi_u32_b32 v98, -1, v98
	v_lshl_add_u32 v98, v98, 4, s99
	ds_read_b128 v[162:165], v98 offset:1024
	s_branch .Lxl_d_1
.Lxl_g_1:
	global_load_dwordx4 v[162:165], v[98:99], off
.Lxl_d_1:
	v_lshl_add_u64 v[98:99], v[0:1], 1, s[10:11]
	v_add_u32_e32 v0, v119, v242
	s_cmp_eq_u32 s98, 0
	s_cbranch_scc1 .Lxl_g_2
	v_mbcnt_lo_u32_b32 v98, -1, 0
	v_mbcnt_hi_u32_b32 v98, -1, v98
	v_lshl_add_u32 v98, v98, 4, s99
	ds_read_b128 v[138:141], v98 offset:2048
	s_branch .Lxl_d_2
.Lxl_g_2:
	global_load_dwordx4 v[138:141], v[98:99], off
.Lxl_d_2:
	v_lshl_add_u64 v[98:99], v[0:1], 1, s[10:11]
	global_load_dwordx4 v[114:117], v[98:99], off
	v_add_u32_e32 v98, 0x4000, v0
	v_mov_b32_e32 v99, v1
	v_lshl_add_u64 v[98:99], v[98:99], 1, s[10:11]
	v_add_u32_e32 v0, 0x8000, v0
	global_load_dwordx4 v[102:105], v[98:99], off
	v_lshl_add_u64 v[98:99], v[0:1], 1, s[10:11]
	global_load_dwordx4 v[98:101], v[98:99], off
	s_cmp_lt_i32 s16, 42
	s_cselect_b32 s0, s0, s1
	s_bitcmp1_b32 s0, 0
	s_cselect_b64 s[4:5], -1, 0
	s_mul_i32 s68, s12, 0x1800
	s_movk_i32 s0, 0x1fff
	s_and_b64 vcc, exec, s[4:5]
	v_mov_b64_e32 v[106:107], s[68:69]
	v_cmp_lt_i32_e64 s[0:1], s0, v249
	s_cbranch_vccnz .LBB0_896
	s_add_i32 s12, s14, 0xffffe000
	s_lshr_b32 s12, s12, 10
	s_mulk_i32 s12, 0x1800
	s_addk_i32 s12, 0x1800
	v_mov_b32_e32 v0, s12
	v_cndmask_b32_e64 v0, 0, v0, s[0:1]
	v_mov_b64_e32 v[106:107], v[0:1]

.LBB0_952:
	v_lshlrev_b64 v[2:3], 1, v[0:1]
	v_cvt_pk_bf16_f32 v118, v52, v53
	v_cvt_pk_bf16_f32 v119, v54, v55
	v_cvt_pk_bf16_f32 v120, v56, v57
	v_cvt_pk_bf16_f32 v121, v58, v59
	v_lshl_add_u64 v[112:113], s[10:11], 0, v[2:3]
	v_mbcnt_lo_u32_b32 v112, -1, 0
	v_mbcnt_hi_u32_b32 v112, -1, v112
	v_lshl_add_u32 v112, v112, 4, s99
	ds_write_b128 v112, v[118:121]
	v_lshl_add_u64 v[2:3], s[78:79], 0, v[2:3]
	v_pk_fma_f32 v[112:113], v[54:55], v[30:31], v[22:23]
	v_pk_fma_f32 v[118:119], v[52:53], v[28:29], v[20:21]
	v_pk_fma_f32 v[120:121], v[56:57], v[44:45], v[24:25]
	v_pk_fma_f32 v[122:123], v[58:59], v[46:47], v[26:27]
	v_cvt_pk_bf16_f32 v118, v118, v119
	v_cvt_pk_bf16_f32 v119, v112, v113
	v_cvt_pk_bf16_f32 v120, v120, v121
	s_nop 0
	v_cvt_pk_bf16_f32 v121, v122, v123
	global_store_dwordx4 v[2:3], v[118:121], off
	s_branch .LBB0_954

.LBB0_957:
	v_lshlrev_b64 v[2:3], 1, v[0:1]
	v_cvt_pk_bf16_f32 v118, v52, v53
	v_cvt_pk_bf16_f32 v119, v54, v55
	v_cvt_pk_bf16_f32 v120, v56, v57
	v_cvt_pk_bf16_f32 v121, v58, v59
	v_lshl_add_u64 v[122:123], s[10:11], 0, v[2:3]
	v_mbcnt_lo_u32_b32 v122, -1, 0
	v_mbcnt_hi_u32_b32 v122, -1, v122
	v_lshl_add_u32 v122, v122, 4, s99
	ds_write_b128 v122, v[118:121] offset:1024
	v_lshl_add_u64 v[2:3], s[78:79], 0, v[2:3]
	s_nop 0
	v_pk_fma_f32 v[120:121], v[54:55], v[42:43], v[34:35]
	v_pk_fma_f32 v[118:119], v[52:53], v[40:41], v[32:33]
	v_pk_fma_f32 v[122:123], v[58:59], v[50:51], v[38:39]
	v_pk_fma_f32 v[124:125], v[56:57], v[48:49], v[36:37]
	v_cvt_pk_bf16_f32 v118, v118, v119
	v_cvt_pk_bf16_f32 v119, v120, v121
	v_cvt_pk_bf16_f32 v121, v122, v123
	s_nop 0
	v_cvt_pk_bf16_f32 v120, v124, v125
	global_store_dwordx4 v[2:3], v[118:121], off
	s_branch .LBB0_959

.LBB0_962:
	v_lshlrev_b64 v[2:3], 1, v[0:1]
	v_cvt_pk_bf16_f32 v118, v24, v25
	v_cvt_pk_bf16_f32 v119, v26, v27
	v_cvt_pk_bf16_f32 v120, v56, v57
	v_cvt_pk_bf16_f32 v121, v58, v59
	v_lshl_add_u64 v[122:123], s[10:11], 0, v[2:3]
	v_mbcnt_lo_u32_b32 v122, -1, 0
	v_mbcnt_hi_u32_b32 v122, -1, v122
	v_lshl_add_u32 v122, v122, 4, s99
	ds_write_b128 v122, v[118:121] offset:2048
	v_lshl_add_u64 v[2:3], s[78:79], 0, v[2:3]
	s_nop 0
	v_pk_fma_f32 v[120:121], v[26:27], v[46:47], v[22:23]
	v_pk_fma_f32 v[118:119], v[24:25], v[44:45], v[20:21]
	v_pk_fma_f32 v[122:123], v[58:59], v[54:55], v[30:31]
	v_pk_fma_f32 v[124:125], v[56:57], v[52:53], v[28:29]
	v_cvt_pk_bf16_f32 v118, v118, v119
	v_cvt_pk_bf16_f32 v119, v120, v121
	v_cvt_pk_bf16_f32 v121, v122, v123
	s_nop 0
	v_cvt_pk_bf16_f32 v120, v124, v125
	global_store_dwordx4 v[2:3], v[118:121], off
	s_branch .LBB0_964

	.amdhsa_kernel _Z14fwd_megakernel6Params
		.amdhsa_group_segment_fixed_size 32752
		.amdhsa_private_segment_fixed_size 0
		.amdhsa_kernarg_size 480
		.amdhsa_user_sgpr_count 2
		.amdhsa_user_sgpr_dispatch_ptr 0
		.amdhsa_user_sgpr_queue_ptr 0
		.amdhsa_user_sgpr_kernarg_segment_ptr 1
		.amdhsa_user_sgpr_dispatch_id 0
		.amdhsa_user_sgpr_kernarg_preload_length 0
		.amdhsa_user_sgpr_kernarg_preload_offset 0
		.amdhsa_user_sgpr_private_segment_size 0
		.amdhsa_uses_dynamic_stack 0
		.amdhsa_enable_private_segment 0
		.amdhsa_system_sgpr_workgroup_id_x 1
		.amdhsa_system_sgpr_workgroup_id_y 0
		.amdhsa_system_sgpr_workgroup_id_z 0
		.amdhsa_system_sgpr_workgroup_info 0
		.amdhsa_system_vgpr_workitem_id 2
		.amdhsa_next_free_vgpr 256
		.amdhsa_next_free_sgpr 102
		.amdhsa_accum_offset 256
		.amdhsa_reserve_vcc 1
		.amdhsa_float_round_mode_32 0
		.amdhsa_float_round_mode_16_64 0
		.amdhsa_float_denorm_mode_32 3
		.amdhsa_float_denorm_mode_16_64 3
		.amdhsa_dx10_clamp 1
		.amdhsa_ieee_mode 1
		.amdhsa_fp16_overflow 0
		.amdhsa_tg_split 0
		.amdhsa_exception_fp_ieee_invalid_op 0
		.amdhsa_exception_fp_denorm_src 0
		.amdhsa_exception_fp_ieee_div_zero 0
		.amdhsa_exception_fp_ieee_overflow 0
		.amdhsa_exception_fp_ieee_underflow 0
		.amdhsa_exception_fp_ieee_inexact 0
		.amdhsa_exception_int_div_zero 0
	.end_amdhsa_kernel

amdhsa.kernels:
  - .agpr_count:     0
    .args:
      - .offset:         0
        .size:           224
        .value_kind:     by_value
      - .offset:         224
        .size:           4
        .value_kind:     hidden_block_count_x
      - .offset:         228
        .size:           4
        .value_kind:     hidden_block_count_y
      - .offset:         232
        .size:           4
        .value_kind:     hidden_block_count_z
      - .offset:         236
        .size:           2
        .value_kind:     hidden_group_size_x
      - .offset:         238
        .size:           2
        .value_kind:     hidden_group_size_y
      - .offset:         240
        .size:           2
        .value_kind:     hidden_group_size_z
      - .offset:         242
        .size:           2
        .value_kind:     hidden_remainder_x
      - .offset:         244
        .size:           2
        .value_kind:     hidden_remainder_y
      - .offset:         246
        .size:           2
        .value_kind:     hidden_remainder_z
      - .offset:         264
        .size:           8
        .value_kind:     hidden_global_offset_x
      - .offset:         272
        .size:           8
        .value_kind:     hidden_global_offset_y
      - .offset:         280
        .size:           8
        .value_kind:     hidden_global_offset_z
      - .offset:         288
        .size:           2
        .value_kind:     hidden_grid_dims
      - .offset:         312
        .size:           8
        .value_kind:     hidden_multigrid_sync_arg
      - .offset:         344
        .size:           4
        .value_kind:     hidden_dynamic_lds_size
    .group_segment_fixed_size: 32752
    .kernarg_segment_align: 8
    .kernarg_segment_size: 480
    .language:       OpenCL C
    .language_version:
      - 2
      - 0
    .max_flat_workgroup_size: 512
    .name:           _Z14fwd_megakernel6Params
    .private_segment_fixed_size: 0
    .sgpr_count:     104
    .sgpr_spill_count: 97
    .symbol:         _Z14fwd_megakernel6Params.kd
    .uniform_work_group_size: 1
    .uses_dynamic_stack: false
    .vgpr_count:     256
    .vgpr_spill_count: 0
    .wavefront_size: 64
